# scan workgroups leave P3 right after their chains (no bias-table setup, no empty tickets)
# speedup vs baseline: 1.0121x; 1.0121x over previous
; #define REP(k) _Pragma("unroll") for (int rep_ = 0; rep_ < ((PROBE_REP == (k)) ? 2 : 1); ++rep_)
; __global__ void __launch_bounds__(NWAVES * 64, 2) fwd_kernel(Params P) {
;     ...
;             __syncthreads();
;             REP(30) { scan_prompt_wg(P, lds, (int)blockIdx.x >> 3, (int)blockIdx.x & 7, wave, lane); __syncthreads(); }
;             __syncthreads();
;         }
;         attn_setup(P, lds, tid);
.LBB0_683:
	s_waitcnt lgkmcnt(0)
	s_barrier
	s_barrier
	s_mov_b64 s[6:7], -1
	s_branch .LBB0_746
